# v026 + bundle of four independent, individually noise-level changes: barrier leader tail (no XGEN bump, acquire before release), hand-written P6 epilogue, attention next-block loads before the LDS-wri
# baseline (speedup 1.0000x reference)
; #define ATT_LOADKV(dst, nn) do { const bf16* src_ = qcol + (rowbase + (size_t)(128 * (nn) + srow) * dil) * NQKV + 1024 + sch * 8; const size_t st_ = (size_t)32 * dil * NQKV; \
;         _Pragma("unroll") for (int i_ = 0; i_ < 4; ++i_) { dst[i_] = __builtin_nontemporal_load((const v4u*)(src_ + i_ * st_)); dst[4 + i_] = __builtin_nontemporal_load((const v4u*)(src_ + i_ * st_ + 1024)); } } while (0)
; #define ATT_LOADQ(nn) do { const bf16* src_ = qcol + (rowbase + (size_t)(128 * (nn) + 16 * w + lq) * dil) * NQKV + 8 * gq; \
;         _Pragma("unroll") for (int s_ = 0; s_ < 4; ++s_) qn[s_] = __builtin_nontemporal_load((const bf16x8*)(src_ + 32 * s_)); } while (0)
; #define ATT_WRITEKV(slot) do { LAS unsigned char* dk_ = lds + (slot) * SLOTB + sdst; LAS unsigned char* dv_ = lds + (slot) * SLOTB + sdstv; \
;         _Pragma("unroll") for (int i_ = 0; i_ < 4; ++i_) { *(LAS v4u*)(dk_ + 8192 * i_) = kv[i_]; *(LAS v4u*)(dv_ + 8192 * i_) = kv[4 + i_]; } } while (0)
; __device__ __forceinline__ void segment(LAS unsigned char* lds, const bf16* __restrict__ QKV, bf16* __restrict__ Og, float* __restrict__ L2, int bl, int g, int h, int r, int dil, int n0, int cnt, int tid) {
;     ...
;     __syncthreads();
;     v4u kv2[8];
;     if (n0 > 0) { ATT_LOADKV(kv, n0 - 1); ATT_LOADKV(kv2, n0); ATT_LOADQ(n0); ATT_WRITEKV((n0 - 1) & 1);
.LBB0_291:
	v_readlane_b32 s0, v238, 3
	s_add_i32 s40, s47, s0
	v_readlane_b32 s0, v238, 4
	v_readfirstlane_b32 s20, v154
	v_readlane_b32 s1, v238, 5
	s_lshr_b32 s21, s20, 6
	s_andn2_b64 vcc, exec, s[0:1]
	v_add_u32_e32 v0, 0, v127
	v_add_u32_e32 v1, 0, v136
	s_barrier
	s_cbranch_vccnz .LBB0_300
	v_lshl_add_u64 v[4:5], v[86:87], 0, s[40:41]
	s_movk_i32 s23, 0x4800
	v_mad_u64_u32 v[6:7], s[0:1], v4, s23, v[90:91]
	v_mov_b32_e32 v2, v7
	v_mad_u64_u32 v[4:5], s[0:1], v5, s23, v[2:3]
	v_readlane_b32 s0, v238, 6
	v_add_u32_e32 v2, s40, v181
	s_movk_i32 s22, 0x2400
	v_readlane_b32 s1, v238, 7
	v_mul_lo_u32 v2, v2, s22
	s_lshl_b32 s22, s21, 4
	v_mov_b32_e32 v7, v4
	s_mov_b64 s[24:25], 0x800
	s_lshl_b64 s[0:1], s[0:1], 1
	v_readlane_b32 s26, v238, 9
	v_lshl_add_u64 v[12:13], v[2:3], 1, v[90:91]
	v_add_u32_e32 v2, s22, v182
	v_mov_b64_e32 v[46:47], s[40:41]
	v_lshl_add_u64 v[4:5], v[6:7], 0, s[24:25]
	global_load_dwordx4 v[48:51], v[6:7], off offset:2048 nt
	v_lshl_add_u64 v[6:7], v[6:7], 0, s[0:1]
	v_readlane_b32 s27, v238, 10
	v_lshl_add_u64 v[20:21], v[12:13], 0, s[0:1]
	v_mad_u64_u32 v[46:47], s[0:1], v2, s54, v[46:47]
	v_lshl_add_u64 v[8:9], v[6:7], 0, s[24:25]
	global_load_dwordx4 v[102:105], v[4:5], off offset:2048 nt
	global_load_dwordx4 v[106:109], v[6:7], off offset:2048 nt
	v_lshl_add_u64 v[4:5], v[6:7], 0, s[26:27]
	v_lshl_add_u64 v[28:29], v[20:21], 0, s[26:27]
	v_mad_u64_u32 v[64:65], s[0:1], v46, s23, v[88:89]
	v_lshl_add_u64 v[6:7], v[4:5], 0, s[24:25]
	global_load_dwordx4 v[110:113], v[8:9], off offset:2048 nt
	global_load_dwordx4 v[114:117], v[4:5], off offset:2048 nt
	v_lshl_add_u64 v[4:5], v[4:5], 0, s[26:27]
	v_lshl_add_u64 v[8:9], v[12:13], 0, s[24:25]
	v_lshl_add_u64 v[16:17], v[20:21], 0, s[24:25]
	v_lshl_add_u64 v[24:25], v[28:29], 0, s[24:25]
	v_mov_b32_e32 v2, v65
	v_lshl_add_u64 v[44:45], v[4:5], 0, s[24:25]
	global_load_dwordx4 v[36:39], v[6:7], off offset:2048 nt
	global_load_dwordx4 v[40:43], v[4:5], off offset:2048 nt
	s_nop 0
	global_load_dwordx4 v[4:7], v[12:13], off offset:2048 nt
	s_nop 0
	global_load_dwordx4 v[8:11], v[8:9], off offset:2048 nt
	s_nop 0
	global_load_dwordx4 v[12:15], v[20:21], off offset:2048 nt
	s_nop 0
	global_load_dwordx4 v[16:19], v[16:17], off offset:2048 nt
	s_nop 0
	global_load_dwordx4 v[20:23], v[28:29], off offset:2048 nt
	s_nop 0
	global_load_dwordx4 v[24:27], v[24:25], off offset:2048 nt
	v_lshl_add_u64 v[28:29], v[28:29], 0, s[26:27]
	v_mad_u64_u32 v[46:47], s[0:1], v47, s23, v[2:3]
	v_lshl_add_u64 v[32:33], v[28:29], 0, s[24:25]
	v_mov_b32_e32 v65, v46
	global_load_dwordx4 v[28:31], v[28:29], off offset:2048 nt
	s_nop 0
	global_load_dwordx4 v[32:35], v[32:33], off offset:2048 nt
	s_nop 0
	global_load_dwordx4 v[52:55], v[64:65], off nt
	global_load_dwordx4 v[56:59], v[64:65], off offset:64 nt
	global_load_dwordx4 v[60:63], v[64:65], off offset:128 nt
	s_nop 0
	global_load_dwordx4 v[64:67], v[64:65], off offset:192 nt
	s_nop 0
	global_load_dwordx4 v[44:47], v[44:45], off offset:2048 nt
	v_or_b32_e32 v2, s22, v119
	s_waitcnt vmcnt(19)
	ds_write_b128 v0, v[48:51] offset:32768
	s_waitcnt vmcnt(18)
	ds_write_b128 v1, v[102:105] offset:32768
	s_waitcnt vmcnt(17)
	ds_write_b128 v0, v[106:109] offset:40960
	s_waitcnt vmcnt(16)
	ds_write_b128 v1, v[110:113] offset:40960
	s_waitcnt vmcnt(15)
	ds_write_b128 v0, v[114:117] offset:49152
	s_cbranch_execnz .LBB0_294

; #define ATT_LOADKV(dst, nn) do { const bf16* src_ = qcol + (rowbase + (size_t)(128 * (nn) + srow) * dil) * NQKV + 1024 + sch * 8; const size_t st_ = (size_t)32 * dil * NQKV; \
;         _Pragma("unroll") for (int i_ = 0; i_ < 4; ++i_) { dst[i_] = __builtin_nontemporal_load((const v4u*)(src_ + i_ * st_)); dst[4 + i_] = __builtin_nontemporal_load((const v4u*)(src_ + i_ * st_ + 1024)); } } while (0)
; #define ATT_LOADQ(nn) do { const bf16* src_ = qcol + (rowbase + (size_t)(128 * (nn) + 16 * w + lq) * dil) * NQKV + 8 * gq; \
;         _Pragma("unroll") for (int s_ = 0; s_ < 4; ++s_) qn[s_] = __builtin_nontemporal_load((const bf16x8*)(src_ + 32 * s_)); } while (0)
; #define ATT_WRITEKV(slot) do { LAS unsigned char* dk_ = lds + (slot) * SLOTB + sdst; LAS unsigned char* dv_ = lds + (slot) * SLOTB + sdstv; \
;         _Pragma("unroll") for (int i_ = 0; i_ < 4; ++i_) { *(LAS v4u*)(dk_ + 8192 * i_) = kv[i_]; *(LAS v4u*)(dv_ + 8192 * i_) = kv[4 + i_]; } } while (0)
; __device__ __forceinline__ void segment(LAS unsigned char* lds, const bf16* __restrict__ QKV, bf16* __restrict__ Og, float* __restrict__ L2, int bl, int g, int h, int r, int dil, int n0, int cnt, int tid) {
;     ...
;     __syncthreads();
;     v4u kv2[8];
;     if (n0 > 0) { ATT_LOADKV(kv, n0 - 1); ATT_LOADKV(kv2, n0); ATT_LOADQ(n0); ATT_WRITEKV((n0 - 1) & 1);
.LBB0_445:
	v_readlane_b32 s0, v238, 3
	s_add_i32 s40, s47, s0
	v_readlane_b32 s0, v238, 4
	v_readfirstlane_b32 s20, v154
	v_readlane_b32 s1, v238, 5
	s_lshr_b32 s21, s20, 6
	s_andn2_b64 vcc, exec, s[0:1]
	v_add_u32_e32 v0, 0, v127
	v_add_u32_e32 v1, 0, v136
	s_barrier
	s_cbranch_vccnz .LBB0_454
	v_lshl_add_u64 v[4:5], v[86:87], 0, s[40:41]
	s_movk_i32 s23, 0x4800
	v_mad_u64_u32 v[6:7], s[0:1], v4, s23, v[90:91]
	v_mov_b32_e32 v2, v7
	v_mad_u64_u32 v[4:5], s[0:1], v5, s23, v[2:3]
	v_readlane_b32 s0, v238, 6
	v_add_u32_e32 v2, s40, v182
	s_movk_i32 s22, 0x2400
	v_readlane_b32 s1, v238, 7
	v_mul_lo_u32 v2, v2, s22
	s_lshl_b32 s22, s21, 4
	v_mov_b32_e32 v7, v4
	s_mov_b64 s[24:25], 0x800
	s_lshl_b64 s[0:1], s[0:1], 1
	v_readlane_b32 s26, v238, 9
	v_lshl_add_u64 v[12:13], v[2:3], 1, v[90:91]
	v_add_u32_e32 v2, s22, v183
	v_mov_b64_e32 v[46:47], s[40:41]
	v_lshl_add_u64 v[4:5], v[6:7], 0, s[24:25]
	global_load_dwordx4 v[48:51], v[6:7], off offset:2048 nt
	v_lshl_add_u64 v[6:7], v[6:7], 0, s[0:1]
	v_readlane_b32 s27, v238, 10
	v_lshl_add_u64 v[20:21], v[12:13], 0, s[0:1]
	v_mad_u64_u32 v[46:47], s[0:1], v2, s54, v[46:47]
	v_lshl_add_u64 v[8:9], v[6:7], 0, s[24:25]
	global_load_dwordx4 v[102:105], v[4:5], off offset:2048 nt
	global_load_dwordx4 v[106:109], v[6:7], off offset:2048 nt
	v_lshl_add_u64 v[4:5], v[6:7], 0, s[26:27]
	v_lshl_add_u64 v[28:29], v[20:21], 0, s[26:27]
	v_mad_u64_u32 v[64:65], s[0:1], v46, s23, v[88:89]
	v_lshl_add_u64 v[6:7], v[4:5], 0, s[24:25]
	global_load_dwordx4 v[110:113], v[8:9], off offset:2048 nt
	global_load_dwordx4 v[114:117], v[4:5], off offset:2048 nt
	v_lshl_add_u64 v[4:5], v[4:5], 0, s[26:27]
	v_lshl_add_u64 v[8:9], v[12:13], 0, s[24:25]
	v_lshl_add_u64 v[16:17], v[20:21], 0, s[24:25]
	v_lshl_add_u64 v[24:25], v[28:29], 0, s[24:25]
	v_mov_b32_e32 v2, v65
	v_lshl_add_u64 v[44:45], v[4:5], 0, s[24:25]
	global_load_dwordx4 v[36:39], v[6:7], off offset:2048 nt
	global_load_dwordx4 v[40:43], v[4:5], off offset:2048 nt
	s_nop 0
	global_load_dwordx4 v[4:7], v[12:13], off offset:2048 nt
	s_nop 0
	global_load_dwordx4 v[8:11], v[8:9], off offset:2048 nt
	s_nop 0
	global_load_dwordx4 v[12:15], v[20:21], off offset:2048 nt
	s_nop 0
	global_load_dwordx4 v[16:19], v[16:17], off offset:2048 nt
	s_nop 0
	global_load_dwordx4 v[20:23], v[28:29], off offset:2048 nt
	s_nop 0
	global_load_dwordx4 v[24:27], v[24:25], off offset:2048 nt
	v_lshl_add_u64 v[28:29], v[28:29], 0, s[26:27]
	v_mad_u64_u32 v[46:47], s[0:1], v47, s23, v[2:3]
	v_lshl_add_u64 v[32:33], v[28:29], 0, s[24:25]
	v_mov_b32_e32 v65, v46
	global_load_dwordx4 v[28:31], v[28:29], off offset:2048 nt
	s_nop 0
	global_load_dwordx4 v[32:35], v[32:33], off offset:2048 nt
	s_nop 0
	global_load_dwordx4 v[52:55], v[64:65], off nt
	global_load_dwordx4 v[56:59], v[64:65], off offset:64 nt
	global_load_dwordx4 v[60:63], v[64:65], off offset:128 nt
	s_nop 0
	global_load_dwordx4 v[64:67], v[64:65], off offset:192 nt
	s_nop 0
	global_load_dwordx4 v[44:47], v[44:45], off offset:2048 nt
	v_or_b32_e32 v2, s22, v119
	s_waitcnt vmcnt(19)
	ds_write_b128 v0, v[48:51] offset:32768
	s_waitcnt vmcnt(18)
	ds_write_b128 v1, v[102:105] offset:32768
	s_waitcnt vmcnt(17)
	ds_write_b128 v0, v[106:109] offset:40960
	s_waitcnt vmcnt(16)
	ds_write_b128 v1, v[110:113] offset:40960
	s_waitcnt vmcnt(15)
	ds_write_b128 v0, v[114:117] offset:49152
	s_cbranch_execnz .LBB0_448
